# replace cooperative-groups grid.sync after the prologue with a single-use flat counter barrier
# baseline (speedup 1.0000x reference)
; #define GBAR() xcd_barrier((unsigned*)(p.ws + WS_BAR), (volatile LAS unsigned*)((LAS unsigned char*)smem + BAR_LDS_OFF))
; template <int PH, int HI>
; DEVI void run_range(const Params& p, unsigned char* smem, cg::grid_group& grid) {
;     ...
;     if constexpr (PH + 1 < HI) { if constexpr (PH == 0) grid.sync(); else GBAR(); run_range<PH + 1, HI>(p, smem, grid); }
.LBB0_120:
	s_or_b64 exec, exec, s[0:1]
	v_lshrrev_b32_e32 v1, 20, v0
	v_lshrrev_b32_e32 v0, 10, v0
	v_or_b32_e32 v0, v0, v1
	s_movk_i32 s0, 0x3ff
	v_and_or_b32 v0, v0, s0, v242
	v_cmp_eq_u32_e32 vcc, 0, v0
	s_waitcnt vmcnt(0)
	s_barrier
	s_and_saveexec_b64 s[0:1], vcc
	s_cbranch_execz .LBB0_130
	buffer_wbl2 sc1
	s_waitcnt vmcnt(0)
	s_add_u32 s2, s96, 0x6ff800
	s_addc_u32 s3, s97, 0
	v_mov_b32_e32 v2, 0
	v_mov_b32_e32 v3, 1
	global_atomic_add v2, v3, s[2:3]
.Lgsync_spin:
	s_sleep 1
	global_load_dword v1, v2, s[2:3] sc1
	s_waitcnt vmcnt(0)
	v_cmp_ne_u32_e32 vcc, s89, v1
	s_cbranch_vccnz .Lgsync_spin
	buffer_inv sc1
	s_waitcnt vmcnt(0)
